# v63_a3_interchunk_mfma_reads_pipelined
# speedup vs baseline: 1.0034x; 1.0034x over previous
; #define LAS __attribute__((address_space(3)))
; #define X make_ctx(lds_raw)
;     ...
;         if (n > 0) {
;             __syncthreads();
;             const bf16_t* sb = (const bf16_t*)kvt + (size_t)unit * 32768;
; #pragma unroll
;             for (int q = 0; q < 8; ++q) { const int sidx = X.tid + 512 * q; const u32x4 wv = *(const u32x4*)(sb + (size_t)sidx * 8);
;                 *(LAS u32x4*)(vT + (sidx >> 4) * GP + (sidx & 15) * 8) = wv; }
;             __syncthreads();
; #pragma unroll
;             for (int ks = 0; ks < 4; ++ks)
; #pragma unroll
;                 for (int nt = 0; nt < 16; ++nt) { const bf16x8 bf = *(const LAS bf16x8*)(vT + (16 * nt + fr) * GP + 32 * ks + 8 * fq); acc[nt] = __builtin_amdgcn_mfma_f32_16x16x32_bf16(afr[ks], bf, acc[nt], 0, 0, 0); }
.LBB0_488:
	s_waitcnt lgkmcnt(0)
	s_barrier
	v_add_u32_e32 v0, v112, v116
	s_waitcnt vmcnt(7)
	ds_write_b128 v85, v[222:225]
	s_waitcnt vmcnt(6)
	ds_write_b128 v184, v[226:229]
	s_waitcnt vmcnt(5)
	ds_write_b128 v185, v[230:233]
	s_waitcnt vmcnt(4)
	ds_write_b128 v191, v[234:237]
	s_waitcnt vmcnt(3)
	ds_write_b128 v192, v[238:241]
	s_waitcnt vmcnt(2)
	ds_write_b128 v193, v[242:245]
	s_waitcnt vmcnt(1)
	ds_write_b128 v194, v[246:249]
	s_waitcnt vmcnt(0)
	ds_write_b128 v195, v[250:253]
	s_waitcnt lgkmcnt(0)
	s_barrier
	ds_read_b128 v[214:217], v0
	ds_read_b128 v[218:221], v0 offset:4352
	ds_read_b128 v[222:225], v0 offset:8704
	ds_read_b128 v[226:229], v0 offset:13056
	s_waitcnt lgkmcnt(3)
	v_mfma_f32_16x16x32_bf16 v[64:67], v[80:83], v[214:217], v[64:67]
	ds_read_b128 v[230:233], v0 offset:17408
	s_waitcnt lgkmcnt(3)
	v_mfma_f32_16x16x32_bf16 v[60:63], v[80:83], v[218:221], v[60:63]
	ds_read_b128 v[214:217], v0 offset:21760
	s_waitcnt lgkmcnt(3)
	v_mfma_f32_16x16x32_bf16 v[52:55], v[80:83], v[222:225], v[52:55]
	ds_read_b128 v[218:221], v205 offset:4352
	s_waitcnt lgkmcnt(3)
	v_mfma_f32_16x16x32_bf16 v[48:51], v[80:83], v[226:229], v[48:51]
	ds_read_b128 v[222:225], v205 offset:8704
	s_waitcnt lgkmcnt(3)
	v_mfma_f32_16x16x32_bf16 v[44:47], v[80:83], v[230:233], v[44:47]
	ds_read_b128 v[226:229], v205 offset:13056
	s_waitcnt lgkmcnt(3)
	v_mfma_f32_16x16x32_bf16 v[40:43], v[80:83], v[214:217], v[40:43]
	ds_read_b128 v[230:233], v205 offset:17408
	s_waitcnt lgkmcnt(3)
	v_mfma_f32_16x16x32_bf16 v[36:39], v[80:83], v[218:221], v[36:39]
	ds_read_b128 v[214:217], v205 offset:21760
	s_waitcnt lgkmcnt(3)
	v_mfma_f32_16x16x32_bf16 v[24:27], v[80:83], v[222:225], v[24:27]
	ds_read_b128 v[218:221], v205 offset:26112
	s_waitcnt lgkmcnt(3)
	v_mfma_f32_16x16x32_bf16 v[20:23], v[80:83], v[226:229], v[20:23]
	ds_read_b128 v[222:225], v205 offset:30464
	s_waitcnt lgkmcnt(3)
	v_mfma_f32_16x16x32_bf16 v[16:19], v[80:83], v[230:233], v[16:19]
	ds_read_b128 v[226:229], v205 offset:34816
	s_waitcnt lgkmcnt(3)
	v_mfma_f32_16x16x32_bf16 v[12:15], v[80:83], v[214:217], v[12:15]
	ds_read_b128 v[230:233], v205 offset:39168
	s_waitcnt lgkmcnt(3)
	v_mfma_f32_16x16x32_bf16 v[8:11], v[80:83], v[218:221], v[8:11]
	ds_read_b128 v[214:217], v205 offset:43520
	s_waitcnt lgkmcnt(3)
	v_mfma_f32_16x16x32_bf16 v[2:5], v[80:83], v[222:225], v[4:7]
	ds_read_b128 v[218:221], v0 offset:64
	s_waitcnt lgkmcnt(3)
	v_mfma_f32_16x16x32_bf16 v[32:35], v[80:83], v[226:229], v[32:35]
	ds_read_b128 v[222:225], v0 offset:4416
	s_waitcnt lgkmcnt(3)
	v_mfma_f32_16x16x32_bf16 v[28:31], v[80:83], v[230:233], v[28:31]
	ds_read_b128 v[226:229], v0 offset:8768
	s_waitcnt lgkmcnt(3)
	v_mfma_f32_16x16x32_bf16 v[56:59], v[80:83], v[214:217], v[56:59]
	ds_read_b128 v[230:233], v0 offset:13120
	s_waitcnt lgkmcnt(3)
	v_mfma_f32_16x16x32_bf16 v[64:67], v[76:79], v[218:221], v[64:67]
	ds_read_b128 v[214:217], v0 offset:17472
	s_waitcnt lgkmcnt(3)
	v_mfma_f32_16x16x32_bf16 v[60:63], v[76:79], v[222:225], v[60:63]
	ds_read_b128 v[218:221], v205 offset:64
	s_waitcnt lgkmcnt(3)
	v_mfma_f32_16x16x32_bf16 v[52:55], v[76:79], v[226:229], v[52:55]
	ds_read_b128 v[222:225], v205 offset:4416
	s_waitcnt lgkmcnt(3)
	v_mfma_f32_16x16x32_bf16 v[48:51], v[76:79], v[230:233], v[48:51]
	ds_read_b128 v[226:229], v205 offset:8768
	s_waitcnt lgkmcnt(3)
	v_mfma_f32_16x16x32_bf16 v[44:47], v[76:79], v[214:217], v[44:47]
	ds_read_b128 v[230:233], v205 offset:13120
	s_waitcnt lgkmcnt(3)
	v_mfma_f32_16x16x32_bf16 v[40:43], v[76:79], v[218:221], v[40:43]
	ds_read_b128 v[214:217], v205 offset:17472
	s_waitcnt lgkmcnt(3)
	v_mfma_f32_16x16x32_bf16 v[36:39], v[76:79], v[222:225], v[36:39]
	ds_read_b128 v[218:221], v205 offset:21824
	s_waitcnt lgkmcnt(3)
	v_mfma_f32_16x16x32_bf16 v[24:27], v[76:79], v[226:229], v[24:27]
	ds_read_b128 v[222:225], v205 offset:26176
	s_waitcnt lgkmcnt(3)
	v_mfma_f32_16x16x32_bf16 v[20:23], v[76:79], v[230:233], v[20:23]
	ds_read_b128 v[226:229], v205 offset:30528
	s_waitcnt lgkmcnt(3)
	v_mfma_f32_16x16x32_bf16 v[16:19], v[76:79], v[214:217], v[16:19]
	ds_read_b128 v[230:233], v205 offset:34880
	s_waitcnt lgkmcnt(3)
	v_mfma_f32_16x16x32_bf16 v[12:15], v[76:79], v[218:221], v[12:15]
	ds_read_b128 v[214:217], v205 offset:39232
	s_waitcnt lgkmcnt(3)
	v_mfma_f32_16x16x32_bf16 v[6:9], v[76:79], v[222:225], v[8:11]
	ds_read_b128 v[218:221], v205 offset:43584
	s_waitcnt lgkmcnt(3)
	v_mfma_f32_16x16x32_bf16 v[2:5], v[76:79], v[226:229], v[2:5]
	ds_read_b128 v[222:225], v0 offset:128
	s_waitcnt lgkmcnt(3)
; #define LAS __attribute__((address_space(3)))
;     ...
; #pragma unroll
;             for (int ks = 0; ks < 4; ++ks)
; #pragma unroll
;                 for (int nt = 0; nt < 16; ++nt) { const bf16x8 bf = *(const LAS bf16x8*)(vT + (16 * nt + fr) * GP + 32 * ks + 8 * fq); acc[nt] = __builtin_amdgcn_mfma_f32_16x16x32_bf16(afr[ks], bf, acc[nt], 0, 0, 0); }
	v_mfma_f32_16x16x32_bf16 v[32:35], v[76:79], v[230:233], v[32:35]
	ds_read_b128 v[226:229], v0 offset:4480
	s_waitcnt lgkmcnt(3)
	v_mfma_f32_16x16x32_bf16 v[28:31], v[76:79], v[214:217], v[28:31]
	ds_read_b128 v[230:233], v0 offset:8832
	s_waitcnt lgkmcnt(3)
	v_mfma_f32_16x16x32_bf16 v[56:59], v[76:79], v[218:221], v[56:59]
	ds_read_b128 v[214:217], v0 offset:13184
	s_waitcnt lgkmcnt(3)
	v_mfma_f32_16x16x32_bf16 v[64:67], v[72:75], v[222:225], v[64:67]
	ds_read_b128 v[218:221], v0 offset:17536
	s_waitcnt lgkmcnt(3)
	v_mfma_f32_16x16x32_bf16 v[60:63], v[72:75], v[226:229], v[60:63]
	ds_read_b128 v[222:225], v205 offset:128
	s_waitcnt lgkmcnt(3)
	v_mfma_f32_16x16x32_bf16 v[52:55], v[72:75], v[230:233], v[52:55]
	ds_read_b128 v[226:229], v205 offset:4480
	s_waitcnt lgkmcnt(3)
	v_mfma_f32_16x16x32_bf16 v[48:51], v[72:75], v[214:217], v[48:51]
	ds_read_b128 v[230:233], v205 offset:8832
	s_waitcnt lgkmcnt(3)
	v_mfma_f32_16x16x32_bf16 v[44:47], v[72:75], v[218:221], v[44:47]
	ds_read_b128 v[214:217], v205 offset:13184
	s_waitcnt lgkmcnt(3)
	v_mfma_f32_16x16x32_bf16 v[40:43], v[72:75], v[222:225], v[40:43]
	ds_read_b128 v[218:221], v205 offset:17536
	s_waitcnt lgkmcnt(3)
	v_mfma_f32_16x16x32_bf16 v[36:39], v[72:75], v[226:229], v[36:39]
	ds_read_b128 v[222:225], v205 offset:21888
	s_waitcnt lgkmcnt(3)
	v_mfma_f32_16x16x32_bf16 v[24:27], v[72:75], v[230:233], v[24:27]
	ds_read_b128 v[226:229], v205 offset:26240
	s_waitcnt lgkmcnt(3)
	v_mfma_f32_16x16x32_bf16 v[20:23], v[72:75], v[214:217], v[20:23]
	ds_read_b128 v[230:233], v205 offset:30592
	s_waitcnt lgkmcnt(3)
	v_mfma_f32_16x16x32_bf16 v[16:19], v[72:75], v[218:221], v[16:19]
	ds_read_b128 v[214:217], v205 offset:34944
	s_waitcnt lgkmcnt(3)
	v_mfma_f32_16x16x32_bf16 v[10:13], v[72:75], v[222:225], v[12:15]
	ds_read_b128 v[218:221], v205 offset:39296
	s_waitcnt lgkmcnt(3)
	v_mfma_f32_16x16x32_bf16 v[6:9], v[72:75], v[226:229], v[6:9]
	ds_read_b128 v[222:225], v205 offset:43648
	s_waitcnt lgkmcnt(3)
	v_mfma_f32_16x16x32_bf16 v[2:5], v[72:75], v[230:233], v[2:5]
	ds_read_b128 v[226:229], v0 offset:192
	s_waitcnt lgkmcnt(3)
	v_mfma_f32_16x16x32_bf16 v[32:35], v[72:75], v[214:217], v[32:35]
	ds_read_b128 v[230:233], v0 offset:4544
	s_waitcnt lgkmcnt(3)
	v_mfma_f32_16x16x32_bf16 v[28:31], v[72:75], v[218:221], v[28:31]
	ds_read_b128 v[214:217], v0 offset:8896
	s_waitcnt lgkmcnt(3)
	v_mfma_f32_16x16x32_bf16 v[56:59], v[72:75], v[222:225], v[56:59]
	ds_read_b128 v[218:221], v0 offset:13248
	s_waitcnt lgkmcnt(3)
	v_mfma_f32_16x16x32_bf16 v[64:67], v[68:71], v[226:229], v[64:67]
	ds_read_b128 v[222:225], v0 offset:17600
	s_waitcnt lgkmcnt(3)
	v_mfma_f32_16x16x32_bf16 v[60:63], v[68:71], v[230:233], v[60:63]
	ds_read_b128 v[226:229], v205 offset:192
	s_waitcnt lgkmcnt(3)
	v_mfma_f32_16x16x32_bf16 v[52:55], v[68:71], v[214:217], v[52:55]
	ds_read_b128 v[230:233], v205 offset:4544
	s_waitcnt lgkmcnt(3)
	v_mfma_f32_16x16x32_bf16 v[48:51], v[68:71], v[218:221], v[48:51]
	ds_read_b128 v[214:217], v205 offset:8896
	s_waitcnt lgkmcnt(3)
	v_mfma_f32_16x16x32_bf16 v[44:47], v[68:71], v[222:225], v[44:47]
	ds_read_b128 v[218:221], v205 offset:13248
	s_waitcnt lgkmcnt(3)
	v_mfma_f32_16x16x32_bf16 v[40:43], v[68:71], v[226:229], v[40:43]
	ds_read_b128 v[222:225], v205 offset:17600
	s_waitcnt lgkmcnt(3)
	v_mfma_f32_16x16x32_bf16 v[36:39], v[68:71], v[230:233], v[36:39]
	ds_read_b128 v[226:229], v205 offset:21952
	s_waitcnt lgkmcnt(3)
	v_mfma_f32_16x16x32_bf16 v[24:27], v[68:71], v[214:217], v[24:27]
	ds_read_b128 v[230:233], v205 offset:26304
	s_waitcnt lgkmcnt(3)
	v_mfma_f32_16x16x32_bf16 v[20:23], v[68:71], v[218:221], v[20:23]
	ds_read_b128 v[214:217], v205 offset:30656
	s_waitcnt lgkmcnt(3)
	v_mfma_f32_16x16x32_bf16 v[16:19], v[68:71], v[222:225], v[16:19]
	ds_read_b128 v[218:221], v205 offset:35008
	s_waitcnt lgkmcnt(3)
	v_mfma_f32_16x16x32_bf16 v[12:15], v[68:71], v[226:229], v[10:13]
	ds_read_b128 v[222:225], v205 offset:39360
	s_waitcnt lgkmcnt(3)
	v_mfma_f32_16x16x32_bf16 v[8:11], v[68:71], v[230:233], v[6:9]
	ds_read_b128 v[226:229], v205 offset:43712
	s_waitcnt lgkmcnt(3)
	v_mfma_f32_16x16x32_bf16 v[4:7], v[68:71], v[214:217], v[2:5]
	s_waitcnt lgkmcnt(2)
	v_mfma_f32_16x16x32_bf16 v[32:35], v[68:71], v[218:221], v[32:35]
	s_waitcnt lgkmcnt(1)
	v_mfma_f32_16x16x32_bf16 v[28:31], v[68:71], v[222:225], v[28:31]
	s_waitcnt lgkmcnt(0)
	v_mfma_f32_16x16x32_bf16 v[56:59], v[68:71], v[226:229], v[56:59]
	s_branch .LBB0_477
